# prep section E (blocked forward substitution) rewritten by hand: all in registers, K=16 bf16 MFMAs consume C-layout results directly (no LDS transposes), prefetched operands, W stored via transposed M
# speedup vs baseline: 1.0353x; 1.0146x over previous
.Lpd_done:
	s_waitcnt lgkmcnt(0)
	s_barrier
	s_ashr_i32 s6, s24, 6
	v_and_b32_e32 v1, 15, v134
	v_lshrrev_b32_e32 v3, 4, v134
	v_lshlrev_b32_e32 v4, 5, v1
	v_lshl_add_u32 v4, v3, 3, v4
	v_add_u32_e32 v4, 0x1c400, v4
	v_mul_u32_u24_e32 v5, 0x90, v1
	v_lshl_add_u32 v5, v3, 3, v5
	v_add_u32_e32 v5, 0x11000, v5
	v_lshlrev_b32_e32 v7, 4, v3
	v_add_u32_e32 v7, 0x20500, v7
	s_cmp_gt_i32 s6, 3
	s_cbranch_scc1 .Lpe_w
	s_lshl_b32 s1, s6, 6
	v_mul_u32_u24_e32 v6, 0x440, v3
	v_lshl_add_u32 v6, v1, 1, v6
	v_add_u32_e32 v6, s1, v6
	s_lshl_b32 s1, s6, 12
	v_lshl_add_u32 v9, v134, 3, s1
	s_add_u32 s4, s10, s16
	s_addc_u32 s5, s11, s17
	s_add_u32 s4, s4, 0x17800000
	s_addc_u32 s5, s5, 0
	ds_read_b128 v[10:13], v7 offset:256
	ds_read_u16 v14, v6 offset:34816
	ds_read_u16 v15, v6 offset:35088
	ds_read_u16 v16, v6 offset:35360
	ds_read_u16 v17, v6 offset:35632
	ds_read_u16 v18, v6 offset:34848
	ds_read_u16 v19, v6 offset:35120
	ds_read_u16 v20, v6 offset:35392
	ds_read_u16 v21, v6 offset:35664
	ds_read_b64 v[164:165], v4 offset:0
	ds_read_b128 v[22:25], v7 offset:320
	ds_read_u16 v136, v6 offset:39168
	ds_read_u16 v137, v6 offset:39440
	ds_read_u16 v138, v6 offset:39712
	ds_read_u16 v139, v6 offset:39984
	ds_read_u16 v140, v6 offset:39200
	ds_read_u16 v141, v6 offset:39472
	ds_read_u16 v142, v6 offset:39744
	ds_read_u16 v143, v6 offset:40016
	ds_read_b64 v[180:181], v5 offset:2304
	ds_read_b64 v[204:205], v4 offset:512
	s_waitcnt lgkmcnt(11)
	v_lshlrev_b32_e32 v14, 16, v14
	v_lshlrev_b32_e32 v15, 16, v15
	v_lshlrev_b32_e32 v16, 16, v16
	v_lshlrev_b32_e32 v17, 16, v17
	v_lshlrev_b32_e32 v18, 16, v18
	v_lshlrev_b32_e32 v19, 16, v19
	v_lshlrev_b32_e32 v20, 16, v20
	v_lshlrev_b32_e32 v21, 16, v21
	v_mul_f32_e32 v14, v10, v14
	v_mul_f32_e32 v15, v11, v15
	v_mul_f32_e32 v16, v12, v16
	v_mul_f32_e32 v17, v13, v17
	v_mul_f32_e32 v18, v10, v18
	v_mul_f32_e32 v19, v11, v19
	v_mul_f32_e32 v20, v12, v20
	v_mul_f32_e32 v21, v13, v21
	v_cvt_pk_bf16_f32 v246, v14, v15
	v_cvt_pk_bf16_f32 v247, v16, v17
	v_cvt_pk_bf16_f32 v144, v18, v19
	v_cvt_pk_bf16_f32 v145, v20, v21
	v_mfma_f32_16x16x16_bf16 v[14:17], v[164:165], v[246:247], 0
	s_nop 0
	v_mfma_f32_16x16x16_bf16 v[18:21], v[164:165], v[144:145], 0
	ds_read_b128 v[148:151], v7 offset:384
	ds_read_u16 v160, v6 offset:43520
	ds_read_u16 v161, v6 offset:43792
	ds_read_u16 v162, v6 offset:44064
	ds_read_u16 v163, v6 offset:44336
	ds_read_u16 v168, v6 offset:43552
	ds_read_u16 v169, v6 offset:43824
	ds_read_u16 v170, v6 offset:44096
	ds_read_u16 v171, v6 offset:44368
	ds_read_b64 v[146:147], v5 offset:4608
	ds_read_b64 v[172:173], v5 offset:4640
	ds_read_b64 v[174:175], v4 offset:1024
	v_cvt_pk_bf16_f32 v176, v14, v15
	v_cvt_pk_bf16_f32 v177, v16, v17
	global_store_dwordx2 v9, v[176:177], s[4:5] offset:0 nt
	v_cvt_pk_bf16_f32 v178, v18, v19
	v_cvt_pk_bf16_f32 v179, v20, v21
	global_store_dwordx2 v9, v[178:179], s[4:5] offset:2048 nt
	s_waitcnt lgkmcnt(13)
	v_mfma_f32_16x16x16_bf16 v[184:187], v[180:181], v[176:177], 0
	v_mfma_f32_16x16x16_bf16 v[188:191], v[180:181], v[178:179], 0
	s_waitcnt lgkmcnt(12)
	v_lshlrev_b32_e32 v136, 16, v136
	v_lshlrev_b32_e32 v137, 16, v137
	v_lshlrev_b32_e32 v138, 16, v138
	v_lshlrev_b32_e32 v139, 16, v139
	v_lshlrev_b32_e32 v140, 16, v140
	v_lshlrev_b32_e32 v141, 16, v141
	v_lshlrev_b32_e32 v142, 16, v142
	v_lshlrev_b32_e32 v143, 16, v143
	v_mul_f32_e32 v136, v22, v136
	v_mul_f32_e32 v137, v23, v137
	v_mul_f32_e32 v138, v24, v138
	v_mul_f32_e32 v139, v25, v139
	v_mul_f32_e32 v140, v22, v140
	v_mul_f32_e32 v141, v23, v141
	v_mul_f32_e32 v142, v24, v142
	v_mul_f32_e32 v143, v25, v143
	v_sub_f32_e32 v184, v136, v184
	v_sub_f32_e32 v185, v137, v185
	v_sub_f32_e32 v186, v138, v186
	v_sub_f32_e32 v187, v139, v187
	v_cvt_pk_bf16_f32 v246, v184, v185
	v_cvt_pk_bf16_f32 v247, v186, v187
	v_sub_f32_e32 v188, v140, v188
	v_sub_f32_e32 v189, v141, v189
	v_sub_f32_e32 v190, v142, v190
	v_sub_f32_e32 v191, v143, v191
	v_cvt_pk_bf16_f32 v144, v188, v189
	v_cvt_pk_bf16_f32 v145, v190, v191
	v_mfma_f32_16x16x16_bf16 v[184:187], v[204:205], v[246:247], 0
	s_nop 0
	v_mfma_f32_16x16x16_bf16 v[188:191], v[204:205], v[144:145], 0
	ds_read_b128 v[192:195], v7 offset:448
	ds_read_u16 v196, v6 offset:47872
	ds_read_u16 v197, v6 offset:48144
	ds_read_u16 v198, v6 offset:48416
	ds_read_u16 v199, v6 offset:48688
	ds_read_u16 v200, v6 offset:47904
	ds_read_u16 v201, v6 offset:48176
	ds_read_u16 v202, v6 offset:48448
	ds_read_u16 v203, v6 offset:48720
	ds_read_b64 v[164:165], v5 offset:6912
	ds_read_b64 v[180:181], v5 offset:6944
	ds_read_b64 v[234:235], v5 offset:6976
	ds_read_b64 v[236:237], v4 offset:1536
	v_cvt_pk_bf16_f32 v238, v184, v185
	v_cvt_pk_bf16_f32 v239, v186, v187
	global_store_dwordx2 v9, v[238:239], s[4:5] offset:512 nt
	v_cvt_pk_bf16_f32 v240, v188, v189
	v_cvt_pk_bf16_f32 v241, v190, v191
	global_store_dwordx2 v9, v[240:241], s[4:5] offset:2560 nt
	s_waitcnt lgkmcnt(14)
	v_mfma_f32_16x16x16_bf16 v[242:245], v[146:147], v[176:177], 0
	v_mfma_f32_16x16x16_bf16 v[10:13], v[146:147], v[178:179], 0
	v_mfma_f32_16x16x16_bf16 v[242:245], v[172:173], v[238:239], v[242:245]
	v_mfma_f32_16x16x16_bf16 v[10:13], v[172:173], v[240:241], v[10:13]
	s_waitcnt lgkmcnt(13)
	v_lshlrev_b32_e32 v160, 16, v160
	v_lshlrev_b32_e32 v161, 16, v161
	v_lshlrev_b32_e32 v162, 16, v162
	v_lshlrev_b32_e32 v163, 16, v163
	v_lshlrev_b32_e32 v168, 16, v168
	v_lshlrev_b32_e32 v169, 16, v169
	v_lshlrev_b32_e32 v170, 16, v170
	v_lshlrev_b32_e32 v171, 16, v171
	v_mul_f32_e32 v160, v148, v160
	v_mul_f32_e32 v161, v149, v161
	v_mul_f32_e32 v162, v150, v162
	v_mul_f32_e32 v163, v151, v163
	v_mul_f32_e32 v168, v148, v168
	v_mul_f32_e32 v169, v149, v169
	v_mul_f32_e32 v170, v150, v170
	v_mul_f32_e32 v171, v151, v171
	v_sub_f32_e32 v242, v160, v242
	v_sub_f32_e32 v243, v161, v243
	v_sub_f32_e32 v244, v162, v244
	v_sub_f32_e32 v245, v163, v245
	v_cvt_pk_bf16_f32 v246, v242, v243
	v_cvt_pk_bf16_f32 v247, v244, v245
	v_sub_f32_e32 v10, v168, v10
	v_sub_f32_e32 v11, v169, v11
	v_sub_f32_e32 v12, v170, v12
	v_sub_f32_e32 v13, v171, v13
	v_cvt_pk_bf16_f32 v144, v10, v11
	v_cvt_pk_bf16_f32 v145, v12, v13
	v_mfma_f32_16x16x16_bf16 v[242:245], v[174:175], v[246:247], 0
	s_nop 0
	v_mfma_f32_16x16x16_bf16 v[10:13], v[174:175], v[144:145], 0
	s_nop 5
	v_cvt_pk_bf16_f32 v204, v242, v243
	v_cvt_pk_bf16_f32 v205, v244, v245
	global_store_dwordx2 v9, v[204:205], s[4:5] offset:1024 nt
	v_cvt_pk_bf16_f32 v146, v10, v11
	v_cvt_pk_bf16_f32 v147, v12, v13
	global_store_dwordx2 v9, v[146:147], s[4:5] offset:3072 nt
	s_waitcnt lgkmcnt(1)
	v_mfma_f32_16x16x16_bf16 v[14:17], v[164:165], v[176:177], 0
	v_mfma_f32_16x16x16_bf16 v[18:21], v[164:165], v[178:179], 0
	v_mfma_f32_16x16x16_bf16 v[14:17], v[180:181], v[238:239], v[14:17]
	v_mfma_f32_16x16x16_bf16 v[18:21], v[180:181], v[240:241], v[18:21]
	v_mfma_f32_16x16x16_bf16 v[14:17], v[234:235], v[204:205], v[14:17]
	v_mfma_f32_16x16x16_bf16 v[18:21], v[234:235], v[146:147], v[18:21]
	s_waitcnt lgkmcnt(0)
	v_lshlrev_b32_e32 v196, 16, v196
	v_lshlrev_b32_e32 v197, 16, v197
	v_lshlrev_b32_e32 v198, 16, v198
	v_lshlrev_b32_e32 v199, 16, v199
	v_lshlrev_b32_e32 v200, 16, v200
	v_lshlrev_b32_e32 v201, 16, v201
	v_lshlrev_b32_e32 v202, 16, v202
	v_lshlrev_b32_e32 v203, 16, v203
	v_mul_f32_e32 v196, v192, v196
	v_mul_f32_e32 v197, v193, v197
	v_mul_f32_e32 v198, v194, v198
	v_mul_f32_e32 v199, v195, v199
	v_mul_f32_e32 v200, v192, v200
	v_mul_f32_e32 v201, v193, v201
	v_mul_f32_e32 v202, v194, v202
	v_mul_f32_e32 v203, v195, v203
	v_sub_f32_e32 v14, v196, v14
	v_sub_f32_e32 v15, v197, v15
	v_sub_f32_e32 v16, v198, v16
	v_sub_f32_e32 v17, v199, v17
	v_cvt_pk_bf16_f32 v172, v14, v15
	v_cvt_pk_bf16_f32 v173, v16, v17
	v_sub_f32_e32 v18, v200, v18
	v_sub_f32_e32 v19, v201, v19
	v_sub_f32_e32 v20, v202, v20
	v_sub_f32_e32 v21, v203, v21
	v_cvt_pk_bf16_f32 v246, v18, v19
	v_cvt_pk_bf16_f32 v247, v20, v21
	v_mfma_f32_16x16x16_bf16 v[14:17], v[236:237], v[172:173], 0
	s_nop 0
	v_mfma_f32_16x16x16_bf16 v[18:21], v[236:237], v[246:247], 0
	s_nop 5
	v_cvt_pk_bf16_f32 v144, v14, v15
	v_cvt_pk_bf16_f32 v145, v16, v17
	global_store_dwordx2 v9, v[144:145], s[4:5] offset:1536 nt
	v_cvt_pk_bf16_f32 v174, v18, v19
	v_cvt_pk_bf16_f32 v175, v20, v21
	global_store_dwordx2 v9, v[174:175], s[4:5] offset:3584 nt
	s_branch .Lpe_done
.Lpe_w:
	s_sub_u32 s0, s6, 4
	s_lshl_b32 s1, s0, 6
	v_mul_u32_u24_e32 v6, 0x440, v3
	v_lshl_add_u32 v6, v1, 1, v6
	v_add_u32_e32 v6, s1, v6
	s_lshl_b32 s1, s0, 10
	v_lshrrev_b32_e32 v9, 1, v3
	v_lshlrev_b32_e32 v9, 8, v9
	v_lshl_add_u32 v9, v1, 4, v9
	v_and_b32_e32 v26, 1, v3
	v_lshl_add_u32 v9, v26, 3, v9
	v_add_u32_e32 v9, s1, v9
	s_add_u32 s4, s10, s16
	s_addc_u32 s5, s11, s17
	s_add_u32 s4, s4, 0x11800000
	s_addc_u32 s5, s5, 0
	ds_read_b128 v[10:13], v7 offset:256
	ds_read_b128 v[14:17], v7 offset:0
	ds_read_u16 v18, v6 offset:0
	ds_read_u16 v19, v6 offset:272
	ds_read_u16 v20, v6 offset:544
	ds_read_u16 v21, v6 offset:816
	ds_read_u16 v22, v6 offset:32
	ds_read_u16 v23, v6 offset:304
	ds_read_u16 v24, v6 offset:576
	ds_read_u16 v25, v6 offset:848
	ds_read_b64 v[164:165], v4 offset:0
	ds_read_b128 v[136:139], v7 offset:320
	ds_read_b128 v[140:143], v7 offset:64
	ds_read_u16 v144, v6 offset:4352
	ds_read_u16 v145, v6 offset:4624
	ds_read_u16 v146, v6 offset:4896
	ds_read_u16 v147, v6 offset:5168
	ds_read_u16 v148, v6 offset:4384
	ds_read_u16 v149, v6 offset:4656
	ds_read_u16 v150, v6 offset:4928
	ds_read_u16 v151, v6 offset:5200
	ds_read_b64 v[180:181], v5 offset:2304
	ds_read_b64 v[204:205], v4 offset:512
	s_waitcnt lgkmcnt(12)
	v_mul_f32_e32 v14, 0x3fb8aa3b, v14
	v_mul_f32_e32 v15, 0x3fb8aa3b, v15
	v_mul_f32_e32 v16, 0x3fb8aa3b, v16
	v_mul_f32_e32 v17, 0x3fb8aa3b, v17
	v_exp_f32_e32 v14, v14
	v_exp_f32_e32 v15, v15
	v_exp_f32_e32 v16, v16
	v_exp_f32_e32 v17, v17
	v_lshlrev_b32_e32 v18, 16, v18
	v_lshlrev_b32_e32 v19, 16, v19
	v_lshlrev_b32_e32 v20, 16, v20
	v_lshlrev_b32_e32 v21, 16, v21
	v_lshlrev_b32_e32 v22, 16, v22
	v_lshlrev_b32_e32 v23, 16, v23
	v_lshlrev_b32_e32 v24, 16, v24
	v_lshlrev_b32_e32 v25, 16, v25
	v_mul_f32_e32 v18, v10, v18
	v_mul_f32_e32 v19, v11, v19
	v_mul_f32_e32 v20, v12, v20
	v_mul_f32_e32 v21, v13, v21
	v_mul_f32_e32 v22, v10, v22
	v_mul_f32_e32 v23, v11, v23
	v_mul_f32_e32 v24, v12, v24
	v_mul_f32_e32 v25, v13, v25
	v_mul_f32_e32 v18, v18, v14
	v_mul_f32_e32 v19, v19, v15
	v_mul_f32_e32 v20, v20, v16
	v_mul_f32_e32 v21, v21, v17
	v_mul_f32_e32 v22, v22, v14
	v_mul_f32_e32 v23, v23, v15
	v_mul_f32_e32 v24, v24, v16
	v_mul_f32_e32 v25, v25, v17
	v_cvt_pk_bf16_f32 v246, v18, v19
	v_cvt_pk_bf16_f32 v247, v20, v21
	v_cvt_pk_bf16_f32 v160, v22, v23
	v_cvt_pk_bf16_f32 v161, v24, v25
	v_mfma_f32_16x16x16_bf16 v[18:21], v[164:165], v[246:247], 0
	s_nop 0
	v_mfma_f32_16x16x16_bf16 v[22:25], v[164:165], v[160:161], 0
	v_mfma_f32_16x16x16_bf16 v[168:171], v[246:247], v[164:165], 0
	v_mfma_f32_16x16x16_bf16 v[172:175], v[160:161], v[164:165], 0
	ds_read_b128 v[176:179], v7 offset:384
	ds_read_b128 v[184:187], v7 offset:128
	ds_read_u16 v188, v6 offset:8704
	ds_read_u16 v189, v6 offset:8976
	ds_read_u16 v190, v6 offset:9248
	ds_read_u16 v191, v6 offset:9520
	ds_read_u16 v192, v6 offset:8736
	ds_read_u16 v193, v6 offset:9008
	ds_read_u16 v194, v6 offset:9280
	ds_read_u16 v195, v6 offset:9552
	ds_read_b64 v[162:163], v5 offset:4608
	ds_read_b64 v[196:197], v5 offset:4640
	ds_read_b64 v[198:199], v4 offset:1024
	v_cvt_pk_bf16_f32 v200, v18, v19
	v_cvt_pk_bf16_f32 v201, v20, v21
	v_cvt_pk_bf16_f32 v202, v22, v23
	v_cvt_pk_bf16_f32 v203, v24, v25
	v_cvt_pk_bf16_f32 v168, v168, v169
	v_cvt_pk_bf16_f32 v169, v170, v171
	global_store_dwordx2 v9, v[168:169], s[4:5] offset:0
	v_cvt_pk_bf16_f32 v172, v172, v173
	v_cvt_pk_bf16_f32 v173, v174, v175
	global_store_dwordx2 v9, v[172:173], s[4:5] offset:512
	s_add_u32 s4, s4, 0x1000
	s_addc_u32 s5, s5, 0
	s_waitcnt lgkmcnt(14)
	v_mfma_f32_16x16x16_bf16 v[234:237], v[180:181], v[200:201], 0
	v_mfma_f32_16x16x16_bf16 v[238:241], v[180:181], v[202:203], 0
	s_waitcnt lgkmcnt(13)
	v_mul_f32_e32 v140, 0x3fb8aa3b, v140
	v_mul_f32_e32 v141, 0x3fb8aa3b, v141
	v_mul_f32_e32 v142, 0x3fb8aa3b, v142
	v_mul_f32_e32 v143, 0x3fb8aa3b, v143
	v_exp_f32_e32 v140, v140
	v_exp_f32_e32 v141, v141
	v_exp_f32_e32 v142, v142
	v_exp_f32_e32 v143, v143
	v_lshlrev_b32_e32 v144, 16, v144
	v_lshlrev_b32_e32 v145, 16, v145
	v_lshlrev_b32_e32 v146, 16, v146
	v_lshlrev_b32_e32 v147, 16, v147
	v_lshlrev_b32_e32 v148, 16, v148
	v_lshlrev_b32_e32 v149, 16, v149
	v_lshlrev_b32_e32 v150, 16, v150
	v_lshlrev_b32_e32 v151, 16, v151
	v_mul_f32_e32 v144, v136, v144
	v_mul_f32_e32 v145, v137, v145
	v_mul_f32_e32 v146, v138, v146
	v_mul_f32_e32 v147, v139, v147
	v_mul_f32_e32 v148, v136, v148
	v_mul_f32_e32 v149, v137, v149
	v_mul_f32_e32 v150, v138, v150
	v_mul_f32_e32 v151, v139, v151
	v_mul_f32_e32 v144, v144, v140
	v_mul_f32_e32 v145, v145, v141
	v_mul_f32_e32 v146, v146, v142
	v_mul_f32_e32 v147, v147, v143
	v_mul_f32_e32 v148, v148, v140
	v_mul_f32_e32 v149, v149, v141
	v_mul_f32_e32 v150, v150, v142
	v_mul_f32_e32 v151, v151, v143
	v_sub_f32_e32 v234, v144, v234
	v_sub_f32_e32 v235, v145, v235
	v_sub_f32_e32 v236, v146, v236
	v_sub_f32_e32 v237, v147, v237
	v_cvt_pk_bf16_f32 v246, v234, v235
	v_cvt_pk_bf16_f32 v247, v236, v237
	v_sub_f32_e32 v238, v148, v238
	v_sub_f32_e32 v239, v149, v239
	v_sub_f32_e32 v240, v150, v240
	v_sub_f32_e32 v241, v151, v241
	v_cvt_pk_bf16_f32 v160, v238, v239
	v_cvt_pk_bf16_f32 v161, v240, v241
	v_mfma_f32_16x16x16_bf16 v[234:237], v[204:205], v[246:247], 0
	s_nop 0
	v_mfma_f32_16x16x16_bf16 v[238:241], v[204:205], v[160:161], 0
	v_mfma_f32_16x16x16_bf16 v[242:245], v[246:247], v[204:205], 0
	v_mfma_f32_16x16x16_bf16 v[10:13], v[160:161], v[204:205], 0
	ds_read_b128 v[14:17], v7 offset:448
	ds_read_b128 v[18:21], v7 offset:192
	ds_read_u16 v22, v6 offset:13056
	ds_read_u16 v23, v6 offset:13328
	ds_read_u16 v24, v6 offset:13600
	ds_read_u16 v25, v6 offset:13872
	ds_read_u16 v168, v6 offset:13088
	ds_read_u16 v169, v6 offset:13360
	ds_read_u16 v170, v6 offset:13632
	ds_read_u16 v171, v6 offset:13904
	ds_read_b64 v[164:165], v5 offset:6912
	ds_read_b64 v[180:181], v5 offset:6944
	ds_read_b64 v[172:173], v5 offset:6976
	ds_read_b64 v[174:175], v4 offset:1536
	v_cvt_pk_bf16_f32 v136, v234, v235
	v_cvt_pk_bf16_f32 v137, v236, v237
	v_cvt_pk_bf16_f32 v138, v238, v239
	v_cvt_pk_bf16_f32 v139, v240, v241
	v_cvt_pk_bf16_f32 v242, v242, v243
	v_cvt_pk_bf16_f32 v243, v244, v245
	global_store_dwordx2 v9, v[242:243], s[4:5] offset:0
	v_cvt_pk_bf16_f32 v10, v10, v11
	v_cvt_pk_bf16_f32 v11, v12, v13
	global_store_dwordx2 v9, v[10:11], s[4:5] offset:512
	s_add_u32 s4, s4, 0x1000
	s_addc_u32 s5, s5, 0
	s_waitcnt lgkmcnt(14)
	v_mfma_f32_16x16x16_bf16 v[140:143], v[162:163], v[200:201], 0
	v_mfma_f32_16x16x16_bf16 v[144:147], v[162:163], v[202:203], 0
	v_mfma_f32_16x16x16_bf16 v[140:143], v[196:197], v[136:137], v[140:143]
	v_mfma_f32_16x16x16_bf16 v[144:147], v[196:197], v[138:139], v[144:147]
	s_waitcnt lgkmcnt(14)
	v_mul_f32_e32 v184, 0x3fb8aa3b, v184
	v_mul_f32_e32 v185, 0x3fb8aa3b, v185
	v_mul_f32_e32 v186, 0x3fb8aa3b, v186
	v_mul_f32_e32 v187, 0x3fb8aa3b, v187
	v_exp_f32_e32 v184, v184
	v_exp_f32_e32 v185, v185
	v_exp_f32_e32 v186, v186
	v_exp_f32_e32 v187, v187
	v_lshlrev_b32_e32 v188, 16, v188
	v_lshlrev_b32_e32 v189, 16, v189
	v_lshlrev_b32_e32 v190, 16, v190
	v_lshlrev_b32_e32 v191, 16, v191
	v_lshlrev_b32_e32 v192, 16, v192
	v_lshlrev_b32_e32 v193, 16, v193
	v_lshlrev_b32_e32 v194, 16, v194
	v_lshlrev_b32_e32 v195, 16, v195
	v_mul_f32_e32 v188, v176, v188
	v_mul_f32_e32 v189, v177, v189
	v_mul_f32_e32 v190, v178, v190
	v_mul_f32_e32 v191, v179, v191
	v_mul_f32_e32 v192, v176, v192
	v_mul_f32_e32 v193, v177, v193
	v_mul_f32_e32 v194, v178, v194
	v_mul_f32_e32 v195, v179, v195
	v_mul_f32_e32 v188, v188, v184
	v_mul_f32_e32 v189, v189, v185
	v_mul_f32_e32 v190, v190, v186
	v_mul_f32_e32 v191, v191, v187
	v_mul_f32_e32 v192, v192, v184
	v_mul_f32_e32 v193, v193, v185
	v_mul_f32_e32 v194, v194, v186
	v_mul_f32_e32 v195, v195, v187
	v_sub_f32_e32 v140, v188, v140
	v_sub_f32_e32 v141, v189, v141
	v_sub_f32_e32 v142, v190, v142
	v_sub_f32_e32 v143, v191, v143
	v_cvt_pk_bf16_f32 v246, v140, v141
	v_cvt_pk_bf16_f32 v247, v142, v143
	v_sub_f32_e32 v144, v192, v144
	v_sub_f32_e32 v145, v193, v145
	v_sub_f32_e32 v146, v194, v146
	v_sub_f32_e32 v147, v195, v147
	v_cvt_pk_bf16_f32 v160, v144, v145
	v_cvt_pk_bf16_f32 v161, v146, v147
	v_mfma_f32_16x16x16_bf16 v[140:143], v[198:199], v[246:247], 0
	s_nop 0
	v_mfma_f32_16x16x16_bf16 v[144:147], v[198:199], v[160:161], 0
	v_mfma_f32_16x16x16_bf16 v[148:151], v[246:247], v[198:199], 0
	v_mfma_f32_16x16x16_bf16 v[234:237], v[160:161], v[198:199], 0
	s_nop 3
	v_cvt_pk_bf16_f32 v204, v140, v141
	v_cvt_pk_bf16_f32 v205, v142, v143
	v_cvt_pk_bf16_f32 v162, v144, v145
	v_cvt_pk_bf16_f32 v163, v146, v147
	v_cvt_pk_bf16_f32 v148, v148, v149
	v_cvt_pk_bf16_f32 v149, v150, v151
	global_store_dwordx2 v9, v[148:149], s[4:5] offset:0
	v_cvt_pk_bf16_f32 v234, v234, v235
	v_cvt_pk_bf16_f32 v235, v236, v237
	global_store_dwordx2 v9, v[234:235], s[4:5] offset:512
	s_add_u32 s4, s4, 0x1000
	s_addc_u32 s5, s5, 0
	s_waitcnt lgkmcnt(1)
	v_mfma_f32_16x16x16_bf16 v[238:241], v[164:165], v[200:201], 0
	v_mfma_f32_16x16x16_bf16 v[242:245], v[164:165], v[202:203], 0
	v_mfma_f32_16x16x16_bf16 v[238:241], v[180:181], v[136:137], v[238:241]
	v_mfma_f32_16x16x16_bf16 v[242:245], v[180:181], v[138:139], v[242:245]
	v_mfma_f32_16x16x16_bf16 v[238:241], v[172:173], v[204:205], v[238:241]
	v_mfma_f32_16x16x16_bf16 v[242:245], v[172:173], v[162:163], v[242:245]
	s_waitcnt lgkmcnt(0)
	v_mul_f32_e32 v18, 0x3fb8aa3b, v18
	v_mul_f32_e32 v19, 0x3fb8aa3b, v19
	v_mul_f32_e32 v20, 0x3fb8aa3b, v20
	v_mul_f32_e32 v21, 0x3fb8aa3b, v21
	v_exp_f32_e32 v18, v18
	v_exp_f32_e32 v19, v19
	v_exp_f32_e32 v20, v20
	v_exp_f32_e32 v21, v21
	v_lshlrev_b32_e32 v22, 16, v22
	v_lshlrev_b32_e32 v23, 16, v23
	v_lshlrev_b32_e32 v24, 16, v24
	v_lshlrev_b32_e32 v25, 16, v25
	v_lshlrev_b32_e32 v168, 16, v168
	v_lshlrev_b32_e32 v169, 16, v169
	v_lshlrev_b32_e32 v170, 16, v170
	v_lshlrev_b32_e32 v171, 16, v171
	v_mul_f32_e32 v22, v14, v22
	v_mul_f32_e32 v23, v15, v23
	v_mul_f32_e32 v24, v16, v24
	v_mul_f32_e32 v25, v17, v25
	v_mul_f32_e32 v168, v14, v168
	v_mul_f32_e32 v169, v15, v169
	v_mul_f32_e32 v170, v16, v170
	v_mul_f32_e32 v171, v17, v171
	v_mul_f32_e32 v22, v22, v18
	v_mul_f32_e32 v23, v23, v19
	v_mul_f32_e32 v24, v24, v20
	v_mul_f32_e32 v25, v25, v21
	v_mul_f32_e32 v168, v168, v18
	v_mul_f32_e32 v169, v169, v19
	v_mul_f32_e32 v170, v170, v20
	v_mul_f32_e32 v171, v171, v21
	v_sub_f32_e32 v238, v22, v238
	v_sub_f32_e32 v239, v23, v239
	v_sub_f32_e32 v240, v24, v240
	v_sub_f32_e32 v241, v25, v241
	v_cvt_pk_bf16_f32 v196, v238, v239
	v_cvt_pk_bf16_f32 v197, v240, v241
	v_sub_f32_e32 v242, v168, v242
	v_sub_f32_e32 v243, v169, v243
	v_sub_f32_e32 v244, v170, v244
	v_sub_f32_e32 v245, v171, v245
	v_cvt_pk_bf16_f32 v246, v242, v243
	v_cvt_pk_bf16_f32 v247, v244, v245
	v_mfma_f32_16x16x16_bf16 v[10:13], v[196:197], v[174:175], 0
	s_nop 0
	v_mfma_f32_16x16x16_bf16 v[176:179], v[246:247], v[174:175], 0
	s_nop 5
	v_cvt_pk_bf16_f32 v10, v10, v11
	v_cvt_pk_bf16_f32 v11, v12, v13
	global_store_dwordx2 v9, v[10:11], s[4:5] offset:0
	v_cvt_pk_bf16_f32 v176, v176, v177
	v_cvt_pk_bf16_f32 v177, v178, v179
	global_store_dwordx2 v9, v[176:177], s[4:5] offset:512
.Lpe_done:
	s_mov_b64 s[46:47], 0x8000
	s_branch .LBB0_309

.LBB0_517:
	v_add_u32_e32 v3, 0x20500, v52
	ds_read_b32 v3, v3
	s_waitcnt lgkmcnt(0)
	v_sub_f32_e32 v3, v2, v3
	v_mul_f32_e32 v3, 0x3fb8aa3b, v3
	v_exp_f32_e32 v3, v3
	s_nop 0
	v_mul_f32_e32 v3, v10, v3
	s_or_b64 exec, exec, s[0:1]
	v_mov_b32_e32 v9, 0
	s_and_saveexec_b64 s[0:1], s[4:5]
	s_cbranch_execnz .LBB0_345
	s_branch .LBB0_346
.LBB0_550:
	s_waitcnt vmcnt(0)
	s_barrier
	s_mov_b64 s[0:1], exec
	v_readlane_b32 s2, v248, 18
	v_readlane_b32 s3, v248, 19
	s_and_b64 s[2:3], s[0:1], s[2:3]
	s_mov_b64 exec, s[2:3]
	s_cbranch_execz .LBB0_602
	v_readlane_b32 s2, v251, 2
	s_waitcnt vmcnt(0) expcnt(0) lgkmcnt(0)
	s_nop 0
	v_mov_b32_e32 v1, s2
	ds_read_b32 v3, v1
	v_readlane_b32 s2, v251, 3
	s_waitcnt lgkmcnt(0)
	v_cmp_ne_u32_e32 vcc, 0, v3
	v_mov_b32_e32 v1, s2
	ds_read_b32 v2, v1
	s_cbranch_vccnz .LBB0_566
	s_mov_b32 s8, 1
	s_branch .LBB0_554
